# peer_u expert-dot butterfly reduction via DPP lane exchanges instead of ds_bpermute round trips (on top of the attention loop rewrite)
# speedup vs baseline: 1.0097x; 1.0016x over previous
;   DI uint8_t* xq() const { return (uint8_t*)(ws + OFF_xq); }
; DI void phase_peer_u(const Params& p, int layer, const int WAVE_S) {
;     ...
;   auto load_half = [&](const u32x4& se, u32x4 (&vv)[8]) {
; #pragma unroll
;     for (int it = 0; it < 8; ++it) {
;       const uint32_t e = (se[it >> 1] >> (16 * (it & 1))) & 0xffffu;
;       vv[it] = *(const u32x4*)(ubase + ((e << 7) | coff));
;     }
;   };
;   auto dot_half = [&](const u32x4 (&vv)[8], const u32x4& xq, int (&ds)[8]) {
; #pragma unroll
;     for (int it = 0; it < 8; ++it) {
;       int a = 0;
; #pragma unroll
;       for (int dw = 0; dw < 4; ++dw) a = __builtin_amdgcn_sdot4((int)vv[it][dw], (int)xq[dw], a, false);
;       ds[it] = a;
;     }
;   };
;     ...
;   for (;;) {
;     int lo[8], hi[8];
;     load_half(se1c, vB);
;     dot_half(vA, xc, lo);
;     load_half(se0n, vA);
;     xn = load_x(t + nwv);
;     dot_half(vB, xc, hi);
.LBB0_454:
	v_ashrrev_i32_e32 v47, 31, v46
	v_lshlrev_b64 v[38:39], 8, v[46:47]
	v_lshl_add_u64 v[40:41], v[86:87], 0, v[38:39]
	global_load_dwordx4 v[78:81], v[40:41], off
	s_waitcnt vmcnt(10)
	v_lshlrev_b32_e32 v46, 7, v42
	v_bfe_u32 v42, v42, 16, 16
	v_lshl_or_b32 v42, v42, 7, v82
	global_load_dwordx4 v[70:73], v42, s[46:47]
	v_lshlrev_b32_e32 v42, 7, v43
	v_and_or_b32 v42, v42, s95, v82
	global_load_dwordx4 v[66:69], v42, s[46:47]
	v_bfe_u32 v42, v43, 16, 16
	v_lshl_or_b32 v42, v42, 7, v82
	v_and_or_b32 v46, v46, s95, v82
	global_load_dwordx4 v[62:65], v42, s[46:47]
	v_lshlrev_b32_e32 v42, 7, v44
	global_load_dwordx4 v[74:77], v46, s[46:47]
	v_and_or_b32 v42, v42, s95, v82
	global_load_dwordx4 v[58:61], v42, s[46:47]
	v_bfe_u32 v42, v44, 16, 16
	v_lshl_or_b32 v42, v42, 7, v82
	global_load_dwordx4 v[54:57], v42, s[46:47]
	v_lshlrev_b32_e32 v42, 7, v45
	v_and_or_b32 v42, v42, s95, v82
	global_load_dwordx4 v[50:53], v42, s[46:47]
	v_bfe_u32 v42, v45, 16, 16
	v_lshl_or_b32 v42, v42, 7, v82
	global_load_dwordx4 v[46:49], v42, s[46:47]
	v_mov_b32_e32 v94, v1
	s_waitcnt vmcnt(16)
	v_dot4c_i32_i8_e32 v94, v30, v34
	v_mov_b32_e32 v101, v1
	v_dot4c_i32_i8_e32 v94, v31, v35
	v_mov_b32_e32 v95, v1
	s_waitcnt vmcnt(9)
	v_dot4c_i32_i8_e32 v101, v2, v34
	v_dot4c_i32_i8_e32 v94, v32, v36
	v_dot4c_i32_i8_e32 v95, v26, v34
	v_dot4c_i32_i8_e32 v94, v33, v37
	v_dot4c_i32_i8_e32 v95, v27, v35
	v_mov_b32_e32 v96, v1
	v_dot4c_i32_i8_e32 v95, v28, v36
	v_dot4c_i32_i8_e32 v96, v22, v34
	v_dot4c_i32_i8_e32 v95, v29, v37
	v_dot4c_i32_i8_e32 v96, v23, v35
	v_dot4c_i32_i8_e32 v96, v24, v36
	v_dot4c_i32_i8_e32 v96, v25, v37
	v_mov_b32_e32 v97, v1
	v_mov_b32_e32 v98, v1
	v_mov_b32_e32 v99, v1
	v_mov_b32_e32 v100, v1
	v_dot4c_i32_i8_e32 v97, v18, v34
	v_dot4c_i32_i8_e32 v98, v14, v34
	v_dot4c_i32_i8_e32 v99, v10, v34
	v_dot4c_i32_i8_e32 v100, v6, v34
	v_dot4c_i32_i8_e32 v97, v19, v35
	v_dot4c_i32_i8_e32 v97, v20, v36
	v_dot4c_i32_i8_e32 v98, v15, v35
	v_dot4c_i32_i8_e32 v99, v11, v35
	v_dot4c_i32_i8_e32 v100, v7, v35
	v_dot4c_i32_i8_e32 v101, v3, v35
	v_dot4c_i32_i8_e32 v97, v21, v37
	v_dot4c_i32_i8_e32 v98, v16, v36
	v_dot4c_i32_i8_e32 v98, v17, v37
	v_lshl_add_u64 v[38:39], v[88:89], 0, v[38:39]
	v_dot4c_i32_i8_e32 v99, v12, v36
	v_add_co_u32_e64 v38, s[40:41], s98, v38
	v_dot4c_i32_i8_e32 v99, v13, v37
	s_nop 0
	v_addc_co_u32_e64 v39, s[40:41], 0, v39, s[40:41]
	v_dot4c_i32_i8_e32 v100, v8, v36
	v_dot4c_i32_i8_e32 v101, v4, v36
	global_load_dwordx4 v[38:41], v[38:39], off offset:16
	v_dot4c_i32_i8_e32 v100, v9, v37
	v_dot4c_i32_i8_e32 v101, v5, v37
	s_waitcnt vmcnt(9)
	v_lshlrev_b32_e32 v2, 7, v78
	v_and_or_b32 v2, v2, s95, v82
	global_load_dwordx4 v[30:33], v2, s[46:47]
	v_bfe_u32 v2, v78, 16, 16
	v_lshl_or_b32 v2, v2, 7, v82
	global_load_dwordx4 v[26:29], v2, s[46:47]
	v_lshlrev_b32_e32 v2, 7, v79
	v_and_or_b32 v2, v2, s95, v82
	global_load_dwordx4 v[22:25], v2, s[46:47]
	v_bfe_u32 v2, v79, 16, 16
	v_mov_b32_e32 v79, v1
	v_lshl_or_b32 v2, v2, 7, v82
	global_load_dwordx4 v[18:21], v2, s[46:47]
	s_waitcnt vmcnt(9)
	v_dot4c_i32_i8_e32 v79, v74, v34
	v_mov_b32_e32 v74, v1
	v_dot4c_i32_i8_e32 v74, v70, v34
	v_mov_b32_e32 v70, v1
	v_dot4c_i32_i8_e32 v70, v66, v34
	v_mov_b32_e32 v66, v1
	v_dot4c_i32_i8_e32 v66, v62, v34
	v_mov_b32_e32 v62, v1
	v_dot4c_i32_i8_e32 v79, v75, v35
	s_waitcnt vmcnt(8)
	v_dot4c_i32_i8_e32 v62, v58, v34
	v_mov_b32_e32 v58, v1
	v_dot4c_i32_i8_e32 v79, v76, v36
	s_waitcnt vmcnt(7)
	v_dot4c_i32_i8_e32 v58, v54, v34
	v_mov_b32_e32 v54, v1
	v_dot4c_i32_i8_e32 v79, v77, v37
	s_waitcnt vmcnt(6)
	v_dot4c_i32_i8_e32 v54, v50, v34
	v_mov_b32_e32 v50, v1
	s_waitcnt vmcnt(5)
; DI int shxi(int v, int m, int lane) { return __builtin_amdgcn_ds_bpermute((lane ^ m) << 2, v); }
; DI void phase_peer_u(const Params& p, int layer, const int WAVE_S) {
;     ...
;   auto finish = [&](int token, const int (&lo)[8], const int (&hi)[8]) {
;     int r8[8], r4[4], r2[2];
; #pragma unroll
;     for (int k = 0; k < 8; ++k) {
;       const int send = b2 ? lo[k] : hi[k], keep = b2 ? hi[k] : lo[k];
;       r8[k] = keep + shxi(send, 4, lane);
;     }
; #pragma unroll
;     for (int k = 0; k < 4; ++k) {
;       const int send = b1 ? r8[k] : r8[k + 4], keep = b1 ? r8[k + 4] : r8[k];
;       r4[k] = keep + shxi(send, 2, lane);
;     }
; #pragma unroll
;     for (int k = 0; k < 2; ++k) {
;       const int send = b0 ? r4[k] : r4[k + 2], keep = b0 ? r4[k + 2] : r4[k];
;       r2[k] = keep + shxi(send, 1, lane);
;     }
;     *(uint32_t*)(part + (size_t)token * 128 + 2 * lane) = pk2((float)r2[0], (float)r2[1]);
	v_dot4c_i32_i8_e32 v50, v46, v34
	v_dot4c_i32_i8_e32 v74, v71, v35
	v_dot4c_i32_i8_e32 v74, v72, v36
	v_dot4c_i32_i8_e32 v74, v73, v37
	v_dot4c_i32_i8_e32 v70, v67, v35
	v_dot4c_i32_i8_e32 v66, v63, v35
	v_dot4c_i32_i8_e32 v62, v59, v35
	v_dot4c_i32_i8_e32 v58, v55, v35
	v_dot4c_i32_i8_e32 v54, v51, v35
	v_dot4c_i32_i8_e32 v50, v47, v35
	v_lshlrev_b32_e32 v2, 7, v80
	v_add_u32_e32 v78, s53, v84
	v_and_or_b32 v2, v2, s95, v82
	v_min_i32_e32 v42, 0xffff, v78
	global_load_dwordx4 v[14:17], v2, s[46:47]
	v_bfe_u32 v2, v80, 16, 16
	v_ashrrev_i32_e32 v43, 31, v42
	v_lshl_or_b32 v2, v2, 7, v82
	v_lshlrev_b64 v[42:43], 7, v[42:43]
	global_load_dwordx4 v[10:13], v2, s[46:47]
	v_lshlrev_b32_e32 v2, 7, v81
	v_lshl_add_u64 v[42:43], v[90:91], 0, v[42:43]
	v_dot4c_i32_i8_e32 v70, v68, v36
	v_and_or_b32 v2, v2, s95, v82
	global_load_dwordx4 v[42:45], v[42:43], off
	v_dot4c_i32_i8_e32 v70, v69, v37
	v_dot4c_i32_i8_e32 v66, v64, v36
	v_dot4c_i32_i8_e32 v62, v60, v36
	v_dot4c_i32_i8_e32 v58, v56, v36
	v_dot4c_i32_i8_e32 v54, v52, v36
	v_dot4c_i32_i8_e32 v50, v48, v36
	global_load_dwordx4 v[6:9], v2, s[46:47]
	v_bfe_u32 v2, v81, 16, 16
	v_lshl_or_b32 v2, v2, 7, v82
	global_load_dwordx4 v[2:5], v2, s[46:47]
	v_dot4c_i32_i8_e32 v66, v65, v37
	v_dot4c_i32_i8_e32 v62, v61, v37
	v_dot4c_i32_i8_e32 v58, v57, v37
	v_dot4c_i32_i8_e32 v54, v53, v37
	v_dot4c_i32_i8_e32 v50, v49, v37
	v_cmp_lt_i32_e64 s[40:41], s51, v78
	s_or_b64 s[48:49], s[40:41], s[48:49]
	s_nop 2
	v_cndmask_b32_e32 v34, v94, v79, vcc
	v_cndmask_b32_e32 v94, v79, v94, vcc
	v_cndmask_b32_e32 v35, v95, v74, vcc
	v_cndmask_b32_e32 v95, v74, v95, vcc
	v_cndmask_b32_e32 v36, v96, v70, vcc
	v_cndmask_b32_e32 v96, v70, v96, vcc
	v_cndmask_b32_e32 v37, v97, v66, vcc
	v_cndmask_b32_e32 v97, v66, v97, vcc
	v_cndmask_b32_e32 v46, v98, v62, vcc
	v_cndmask_b32_e32 v98, v62, v98, vcc
	v_cndmask_b32_e32 v47, v99, v58, vcc
	v_cndmask_b32_e32 v99, v58, v99, vcc
	v_cndmask_b32_e32 v48, v100, v54, vcc
	v_cndmask_b32_e32 v100, v54, v100, vcc
	v_cndmask_b32_e32 v49, v101, v50, vcc
	v_cndmask_b32_e32 v101, v50, v101, vcc
	v_mov_b32_dpp v79, v34 row_half_mirror row_mask:0xf bank_mask:0xf
	v_mov_b32_dpp v74, v35 row_half_mirror row_mask:0xf bank_mask:0xf
	v_mov_b32_dpp v70, v36 row_half_mirror row_mask:0xf bank_mask:0xf
	v_mov_b32_dpp v66, v37 row_half_mirror row_mask:0xf bank_mask:0xf
	v_mov_b32_dpp v62, v46 row_half_mirror row_mask:0xf bank_mask:0xf
	v_mov_b32_dpp v58, v47 row_half_mirror row_mask:0xf bank_mask:0xf
	v_mov_b32_dpp v54, v48 row_half_mirror row_mask:0xf bank_mask:0xf
	v_mov_b32_dpp v50, v49 row_half_mirror row_mask:0xf bank_mask:0xf
	v_add_u32_dpp v94, v79, v94 quad_perm:[3,2,1,0] row_mask:0xf bank_mask:0xf
	v_add_u32_dpp v95, v74, v95 quad_perm:[3,2,1,0] row_mask:0xf bank_mask:0xf
	v_add_u32_dpp v96, v70, v96 quad_perm:[3,2,1,0] row_mask:0xf bank_mask:0xf
	v_add_u32_dpp v97, v66, v97 quad_perm:[3,2,1,0] row_mask:0xf bank_mask:0xf
	v_add_u32_dpp v98, v62, v98 quad_perm:[3,2,1,0] row_mask:0xf bank_mask:0xf
	v_add_u32_dpp v99, v58, v99 quad_perm:[3,2,1,0] row_mask:0xf bank_mask:0xf
	v_add_u32_dpp v100, v54, v100 quad_perm:[3,2,1,0] row_mask:0xf bank_mask:0xf
	v_add_u32_dpp v101, v50, v101 quad_perm:[3,2,1,0] row_mask:0xf bank_mask:0xf
	v_cndmask_b32_e64 v34, v94, v98, s[34:35]
	v_cndmask_b32_e64 v94, v98, v94, s[34:35]
	v_cndmask_b32_e64 v35, v95, v99, s[34:35]
	v_cndmask_b32_e64 v95, v99, v95, s[34:35]
	v_cndmask_b32_e64 v36, v96, v100, s[34:35]
	v_cndmask_b32_e64 v96, v100, v96, s[34:35]
	v_cndmask_b32_e64 v37, v97, v101, s[34:35]
	v_cndmask_b32_e64 v97, v101, v97, s[34:35]
	v_add_u32_dpp v94, v34, v94 quad_perm:[2,3,0,1] row_mask:0xf bank_mask:0xf
	v_add_u32_dpp v95, v35, v95 quad_perm:[2,3,0,1] row_mask:0xf bank_mask:0xf
	v_add_u32_dpp v96, v36, v96 quad_perm:[2,3,0,1] row_mask:0xf bank_mask:0xf
	v_add_u32_dpp v97, v37, v97 quad_perm:[2,3,0,1] row_mask:0xf bank_mask:0xf
	s_nop 0
	v_cndmask_b32_e64 v34, v96, v94, s[36:37]
	v_cndmask_b32_e64 v94, v94, v96, s[36:37]
	v_cndmask_b32_e64 v35, v97, v95, s[36:37]
	v_cndmask_b32_e64 v95, v95, v97, s[36:37]
	s_nop 0
	v_add_u32_dpp v94, v34, v94 quad_perm:[1,0,3,2] row_mask:0xf bank_mask:0xf
	v_add_u32_dpp v95, v35, v95 quad_perm:[1,0,3,2] row_mask:0xf bank_mask:0xf
	s_nop 0
	v_cvt_f32_i32_e32 v34, v94
	v_cvt_f32_i32_e32 v35, v95
	v_cvt_pk_bf16_f32 v34, v34, v35
	global_store_dword v[92:93], v34, off
	v_add_u32_e32 v34, s99, v84
	v_min_i32_e32 v46, 0xffff, v34
	s_waitcnt vmcnt(3)
	v_mov_b64_e32 v[34:35], v[42:43]
	v_mov_b64_e32 v[36:37], v[44:45]
	v_mov_b64_e32 v[44:45], v[40:41]
	v_lshl_add_u64 v[92:93], v[92:93], 0, s[0:1]
	v_mov_b64_e32 v[42:43], v[38:39]
	v_mov_b32_e32 v84, v78
	s_andn2_b64 exec, exec, s[48:49]
	s_cbranch_execnz .LBB0_454
